# attention: cross-half row-max exchange (permlane) only on the rescale paths; the wave-uniform check uses per-lane maxima
# speedup vs baseline: 1.0026x; 1.0026x over previous
; DI float rowmax32(const f32x16& p0, const f32x16& p1) {
;     float a = fmaxf(fmaxf(p0[0], p0[1]), p1[0]), b = fmaxf(fmaxf(p0[2], p0[3]), p1[1]); a = fmaxf(fmaxf(a, p1[2]), p1[3]);
; #pragma unroll
;     for (int r = 4; r < 16; r += 4) { a = fmaxf(fmaxf(a, p0[r]), p0[r + 1]); b = fmaxf(fmaxf(b, p0[r + 2]), p0[r + 3]); a = fmaxf(fmaxf(a, p1[r]), p1[r + 1]); b = fmaxf(fmaxf(b, p1[r + 2]), p1[r + 3]); }
;     const float m = fmaxf(a, b);
;     const auto rr = __builtin_amdgcn_permlane32_swap(__float_as_uint(m), __float_as_uint(m), false, false);
;     return fmaxf(__uint_as_float(rr[0]), __uint_as_float(rr[1]));
.Lat1_first:
	s_mov_b64 s[10:11], -1
	v_mov_b32_e32 v84, v83
	s_nop 1
	v_permlane32_swap_b32_e32 v83, v84
	v_max_f32_e32 v83, v83, v84
	v_mov_b32_e32 v84, v83
	s_branch .Lat1_apply
.Lat1_resc:
	s_mov_b64 s[10:11], 0
	v_mov_b32_e32 v84, v83
	s_nop 1
	v_permlane32_swap_b32_e32 v83, v84
	v_max_f32_e32 v83, v83, v84
	v_max_f32_e32 v84, 0, v83

.Lat1_resc_b:
	v_mov_b32_e32 v52, v51
	s_nop 1
	v_permlane32_swap_b32_e32 v51, v52
	v_max_f32_e32 v51, v51, v52
	v_max_f32_e32 v34, v51, v51
	v_max_f32_e32 v35, 0, v34
	v_exp_f32_e64 v36, -v35
	v_mov_b32_e32 v34, v35
	v_add_f32_e32 v205, v204, v35
	v_pk_add_f32 v[82:83], v[82:83], v[34:35] op_sel_hi:[1,0] neg_lo:[0,1] neg_hi:[0,1]
	v_pk_add_f32 v[98:99], v[98:99], v[34:35] op_sel_hi:[1,0] neg_lo:[0,1] neg_hi:[0,1]
	v_pk_add_f32 v[84:85], v[84:85], v[34:35] op_sel_hi:[1,0] neg_lo:[0,1] neg_hi:[0,1]
	v_pk_add_f32 v[100:101], v[100:101], v[34:35] op_sel_hi:[1,0] neg_lo:[0,1] neg_hi:[0,1]
	v_pk_add_f32 v[86:87], v[86:87], v[34:35] op_sel_hi:[1,0] neg_lo:[0,1] neg_hi:[0,1]
	v_pk_add_f32 v[102:103], v[102:103], v[34:35] op_sel_hi:[1,0] neg_lo:[0,1] neg_hi:[0,1]
	v_pk_add_f32 v[88:89], v[88:89], v[34:35] op_sel_hi:[1,0] neg_lo:[0,1] neg_hi:[0,1]
	v_pk_add_f32 v[104:105], v[104:105], v[34:35] op_sel_hi:[1,0] neg_lo:[0,1] neg_hi:[0,1]
	v_pk_add_f32 v[90:91], v[90:91], v[34:35] op_sel_hi:[1,0] neg_lo:[0,1] neg_hi:[0,1]
	v_pk_add_f32 v[106:107], v[106:107], v[34:35] op_sel_hi:[1,0] neg_lo:[0,1] neg_hi:[0,1]
	v_pk_add_f32 v[92:93], v[92:93], v[34:35] op_sel_hi:[1,0] neg_lo:[0,1] neg_hi:[0,1]
	v_pk_add_f32 v[108:109], v[108:109], v[34:35] op_sel_hi:[1,0] neg_lo:[0,1] neg_hi:[0,1]
	v_pk_add_f32 v[94:95], v[94:95], v[34:35] op_sel_hi:[1,0] neg_lo:[0,1] neg_hi:[0,1]
	v_pk_add_f32 v[110:111], v[110:111], v[34:35] op_sel_hi:[1,0] neg_lo:[0,1] neg_hi:[0,1]
	v_pk_add_f32 v[96:97], v[96:97], v[34:35] op_sel_hi:[1,0] neg_lo:[0,1] neg_hi:[0,1]
	v_pk_add_f32 v[112:113], v[112:113], v[34:35] op_sel_hi:[1,0] neg_lo:[0,1] neg_hi:[0,1]
	v_xor_b32_e32 v34, 0x80000000, v205
	v_pk_mul_f32 v[16:17], v[16:17], v[36:37] op_sel_hi:[1,0]
	v_pk_mul_f32 v[14:15], v[14:15], v[36:37] op_sel_hi:[1,0]
	v_pk_mul_f32 v[12:13], v[12:13], v[36:37] op_sel_hi:[1,0]
	v_pk_mul_f32 v[10:11], v[10:11], v[36:37] op_sel_hi:[1,0]
	v_pk_mul_f32 v[8:9], v[8:9], v[36:37] op_sel_hi:[1,0]
	v_pk_mul_f32 v[6:7], v[6:7], v[36:37] op_sel_hi:[1,0]
	v_pk_mul_f32 v[4:5], v[4:5], v[36:37] op_sel_hi:[1,0]
	v_pk_mul_f32 v[2:3], v[2:3], v[36:37] op_sel_hi:[1,0]
	v_pk_mul_f32 v[32:33], v[32:33], v[36:37] op_sel_hi:[1,0]
	v_pk_mul_f32 v[30:31], v[30:31], v[36:37] op_sel_hi:[1,0]
	v_pk_mul_f32 v[28:29], v[28:29], v[36:37] op_sel_hi:[1,0]
	v_pk_mul_f32 v[26:27], v[26:27], v[36:37] op_sel_hi:[1,0]
	v_pk_mul_f32 v[24:25], v[24:25], v[36:37] op_sel_hi:[1,0]
	v_pk_mul_f32 v[22:23], v[22:23], v[36:37] op_sel_hi:[1,0]
	v_pk_mul_f32 v[20:21], v[20:21], v[36:37] op_sel_hi:[1,0]
	v_pk_mul_f32 v[18:19], v[18:19], v[36:37] op_sel_hi:[1,0]
	v_mul_f32_e32 v180, v180, v36
	v_mov_b32_e32 v35, v34
	v_mov_b32_e32 v36, v34
	v_mov_b32_e32 v37, v34
	v_mov_b32_e32 v38, v34
	v_mov_b32_e32 v39, v34
	v_mov_b32_e32 v40, v34
	v_mov_b32_e32 v41, v34
	v_mov_b32_e32 v42, v34
	v_mov_b32_e32 v43, v34
	v_mov_b32_e32 v44, v34
	v_mov_b32_e32 v45, v34
	v_mov_b32_e32 v46, v34
	v_mov_b32_e32 v47, v34
	v_mov_b32_e32 v48, v34
	v_mov_b32_e32 v49, v34
	s_branch .LBB0_820

; DI float rowmax32(const f32x16& p0, const f32x16& p1) {
;     float a = fmaxf(fmaxf(p0[0], p0[1]), p1[0]), b = fmaxf(fmaxf(p0[2], p0[3]), p1[1]); a = fmaxf(fmaxf(a, p1[2]), p1[3]);
; #pragma unroll
;     for (int r = 4; r < 16; r += 4) { a = fmaxf(fmaxf(a, p0[r]), p0[r + 1]); b = fmaxf(fmaxf(b, p0[r + 2]), p0[r + 3]); a = fmaxf(fmaxf(a, p1[r]), p1[r + 1]); b = fmaxf(fmaxf(b, p1[r + 2]), p1[r + 3]); }
;     const float m = fmaxf(a, b);
;     const auto rr = __builtin_amdgcn_permlane32_swap(__float_as_uint(m), __float_as_uint(m), false, false);
;     return fmaxf(__uint_as_float(rr[0]), __uint_as_float(rr[1]));
.LBB0_804:
	s_or_b64 exec, exec, s[8:9]
	global_load_dwordx4 v[146:149], v160, s[56:57] offset:128
	ds_read_b128 v[98:101], v201 offset:13312
	ds_read_b128 v[102:105], v201 offset:13344
	v_max_f32_e32 v83, v50, v51
	v_max3_f32 v84, v52, v53, v67
	v_max3_f32 v83, v83, v66, v68
	v_max3_f32 v83, v83, v69, v54
	v_max3_f32 v84, v84, v56, v57
	v_max3_f32 v83, v83, v55, v70
	v_max3_f32 v84, v84, v72, v73
	v_max3_f32 v83, v83, v71, v58
	v_max3_f32 v84, v84, v60, v61
	v_max3_f32 v83, v83, v59, v74
	v_max3_f32 v84, v84, v76, v77
	v_max3_f32 v83, v83, v75, v62
	v_max3_f32 v84, v84, v64, v65
	v_max3_f32 v83, v83, v63, v78
	v_max3_f32 v84, v84, v80, v81
	v_max3_f32 v83, v83, v79, v84
	s_cmp_eq_u32 s12, 0
	s_cbranch_scc1 .Lat1_first
	v_cmp_lt_f32_e32 vcc, s97, v83
	s_cbranch_vccnz .Lat1_resc
	v_mov_b32_e32 v204, v205

; DI float rowmax32(const f32x16& p0, const f32x16& p1) {
;     float a = fmaxf(fmaxf(p0[0], p0[1]), p1[0]), b = fmaxf(fmaxf(p0[2], p0[3]), p1[1]); a = fmaxf(fmaxf(a, p1[2]), p1[3]);
; #pragma unroll
;     for (int r = 4; r < 16; r += 4) { a = fmaxf(fmaxf(a, p0[r]), p0[r + 1]); b = fmaxf(fmaxf(b, p0[r + 2]), p0[r + 3]); a = fmaxf(fmaxf(a, p1[r]), p1[r + 1]); b = fmaxf(fmaxf(b, p1[r + 2]), p1[r + 3]); }
;     const float m = fmaxf(a, b);
;     const auto rr = __builtin_amdgcn_permlane32_swap(__float_as_uint(m), __float_as_uint(m), false, false);
;     return fmaxf(__uint_as_float(rr[0]), __uint_as_float(rr[1]));
.LBB0_817:
	s_or_b64 exec, exec, s[8:9]
	global_load_dwordx4 v[146:149], v160, s[56:57] offset:256
	ds_read_b128 v[242:245], v201
	ds_read_b128 v[246:249], v201 offset:32
	v_add_f32_e32 v50, v66, v50
	v_add_u32_e32 v150, 0x6000, v150
	v_add_u32_e32 v152, 0x6000, v152
	v_add_u32_e32 v160, 0x100, v160
	v_add_f32_e32 v51, v67, v51
	v_add_f32_e32 v52, v68, v52
	v_add_f32_e32 v50, v51, v50
	v_add_f32_e32 v53, v69, v53
	v_add_f32_e32 v50, v52, v50
	v_add_f32_e32 v54, v70, v54
	v_add_f32_e32 v50, v53, v50
	v_add_f32_e32 v55, v71, v55
	v_add_f32_e32 v50, v54, v50
	v_max_f32_e32 v51, v82, v83
	v_add_f32_e32 v56, v72, v56
	v_add_f32_e32 v50, v55, v50
	v_max3_f32 v52, v84, v85, v99
	v_max3_f32 v51, v51, v98, v100
	v_add_f32_e32 v57, v73, v57
	v_add_f32_e32 v50, v56, v50
	v_max3_f32 v51, v51, v101, v86
	v_max3_f32 v52, v52, v88, v89
	v_add_f32_e32 v58, v74, v58
	v_add_f32_e32 v50, v57, v50
	v_max3_f32 v51, v51, v87, v102
	v_max3_f32 v52, v52, v104, v105
	v_add_f32_e32 v59, v75, v59
	v_add_f32_e32 v50, v58, v50
	v_max3_f32 v51, v51, v103, v90
	v_max3_f32 v52, v52, v92, v93
	v_add_f32_e32 v60, v76, v60
	v_add_f32_e32 v50, v59, v50
	v_max3_f32 v51, v51, v91, v106
	v_max3_f32 v52, v52, v108, v109
	v_add_f32_e32 v61, v77, v61
	v_add_f32_e32 v50, v60, v50
	v_max3_f32 v51, v51, v107, v94
	v_max3_f32 v52, v52, v96, v97
	v_add_f32_e32 v62, v78, v62
	v_add_f32_e32 v50, v61, v50
	v_max3_f32 v51, v51, v95, v110
	v_max3_f32 v52, v52, v112, v113
	v_add_f32_e32 v63, v79, v63
	v_add_f32_e32 v50, v62, v50
	v_max3_f32 v51, v51, v111, v52
	v_add_f32_e32 v64, v80, v64
	v_add_f32_e32 v50, v63, v50
	v_add_f32_e32 v65, v81, v65
	v_add_f32_e32 v50, v64, v50
	v_add_f32_e32 v50, v65, v50
	v_add_f32_e32 v180, v203, v50
	v_cmp_lt_f32_e32 vcc, s97, v51
	s_cbranch_vccnz .Lat1_resc_b
	v_mov_b32_e32 v205, v204

; DI float rowmax32(const f32x16& p0, const f32x16& p1) {
;     float a = fmaxf(fmaxf(p0[0], p0[1]), p1[0]), b = fmaxf(fmaxf(p0[2], p0[3]), p1[1]); a = fmaxf(fmaxf(a, p1[2]), p1[3]);
; #pragma unroll
;     for (int r = 4; r < 16; r += 4) { a = fmaxf(fmaxf(a, p0[r]), p0[r + 1]); b = fmaxf(fmaxf(b, p0[r + 2]), p0[r + 3]); a = fmaxf(fmaxf(a, p1[r]), p1[r + 1]); b = fmaxf(fmaxf(b, p1[r + 2]), p1[r + 3]); }
;     const float m = fmaxf(a, b);
;     const auto rr = __builtin_amdgcn_permlane32_swap(__float_as_uint(m), __float_as_uint(m), false, false);
;     return fmaxf(__uint_as_float(rr[0]), __uint_as_float(rr[1]));
.Lat2_first:
	s_mov_b64 s[10:11], -1
	v_mov_b32_e32 v97, v96
	s_nop 1
	v_permlane32_swap_b32_e32 v96, v97
	v_max_f32_e32 v96, v96, v97
	v_mov_b32_e32 v97, v96
	s_branch .Lat2_apply
.Lat2_resc:
	s_mov_b64 s[10:11], 0
	v_mov_b32_e32 v97, v96
	s_nop 1
	v_permlane32_swap_b32_e32 v96, v97
	v_max_f32_e32 v96, v96, v97
	v_max_f32_e32 v97, 0, v96

.Lat2_resc_b:
	v_mov_b32_e32 v4, v3
	s_nop 1
	v_permlane32_swap_b32_e32 v3, v4
	v_max_f32_e32 v3, v3, v4
	v_max_f32_e32 v3, v3, v3
	v_max_f32_e32 v3, 0, v3
	v_exp_f32_e64 v4, -v3
	v_add_f32_e32 v210, v209, v3
	v_mov_b32_e32 v2, v3
	v_xor_b32_e32 v48, 0x80000000, v210
	v_pk_add_f32 v[96:97], v[96:97], v[2:3] op_sel_hi:[1,0] neg_lo:[0,1] neg_hi:[0,1]
	v_pk_add_f32 v[112:113], v[112:113], v[2:3] op_sel_hi:[1,0] neg_lo:[0,1] neg_hi:[0,1]
	v_pk_add_f32 v[98:99], v[98:99], v[2:3] op_sel_hi:[1,0] neg_lo:[0,1] neg_hi:[0,1]
	v_pk_add_f32 v[114:115], v[114:115], v[2:3] op_sel_hi:[1,0] neg_lo:[0,1] neg_hi:[0,1]
	v_pk_add_f32 v[100:101], v[100:101], v[2:3] op_sel_hi:[1,0] neg_lo:[0,1] neg_hi:[0,1]
	v_pk_add_f32 v[116:117], v[116:117], v[2:3] op_sel_hi:[1,0] neg_lo:[0,1] neg_hi:[0,1]
	v_pk_add_f32 v[102:103], v[102:103], v[2:3] op_sel_hi:[1,0] neg_lo:[0,1] neg_hi:[0,1]
	v_pk_add_f32 v[118:119], v[118:119], v[2:3] op_sel_hi:[1,0] neg_lo:[0,1] neg_hi:[0,1]
	v_pk_add_f32 v[104:105], v[104:105], v[2:3] op_sel_hi:[1,0] neg_lo:[0,1] neg_hi:[0,1]
	v_pk_add_f32 v[120:121], v[120:121], v[2:3] op_sel_hi:[1,0] neg_lo:[0,1] neg_hi:[0,1]
	v_pk_add_f32 v[106:107], v[106:107], v[2:3] op_sel_hi:[1,0] neg_lo:[0,1] neg_hi:[0,1]
	v_pk_add_f32 v[122:123], v[122:123], v[2:3] op_sel_hi:[1,0] neg_lo:[0,1] neg_hi:[0,1]
	v_pk_add_f32 v[108:109], v[108:109], v[2:3] op_sel_hi:[1,0] neg_lo:[0,1] neg_hi:[0,1]
	v_pk_add_f32 v[124:125], v[124:125], v[2:3] op_sel_hi:[1,0] neg_lo:[0,1] neg_hi:[0,1]
	v_pk_add_f32 v[110:111], v[110:111], v[2:3] op_sel_hi:[1,0] neg_lo:[0,1] neg_hi:[0,1]
	v_pk_add_f32 v[126:127], v[126:127], v[2:3] op_sel_hi:[1,0] neg_lo:[0,1] neg_hi:[0,1]
	v_pk_mul_f32 v[46:47], v[46:47], v[4:5] op_sel_hi:[1,0]
	v_pk_mul_f32 v[44:45], v[44:45], v[4:5] op_sel_hi:[1,0]
	v_pk_mul_f32 v[42:43], v[42:43], v[4:5] op_sel_hi:[1,0]
	v_pk_mul_f32 v[40:41], v[40:41], v[4:5] op_sel_hi:[1,0]
	v_pk_mul_f32 v[38:39], v[38:39], v[4:5] op_sel_hi:[1,0]
	v_pk_mul_f32 v[36:37], v[36:37], v[4:5] op_sel_hi:[1,0]
	v_pk_mul_f32 v[34:35], v[34:35], v[4:5] op_sel_hi:[1,0]
	v_pk_mul_f32 v[32:33], v[32:33], v[4:5] op_sel_hi:[1,0]
	v_pk_mul_f32 v[30:31], v[30:31], v[4:5] op_sel_hi:[1,0]
	v_pk_mul_f32 v[28:29], v[28:29], v[4:5] op_sel_hi:[1,0]
	v_pk_mul_f32 v[26:27], v[26:27], v[4:5] op_sel_hi:[1,0]
	v_pk_mul_f32 v[24:25], v[24:25], v[4:5] op_sel_hi:[1,0]
	v_pk_mul_f32 v[22:23], v[22:23], v[4:5] op_sel_hi:[1,0]
	v_pk_mul_f32 v[20:21], v[20:21], v[4:5] op_sel_hi:[1,0]
	v_pk_mul_f32 v[18:19], v[18:19], v[4:5] op_sel_hi:[1,0]
	v_pk_mul_f32 v[16:17], v[16:17], v[4:5] op_sel_hi:[1,0]
	v_mul_f32_e32 v188, v188, v4
	v_mov_b32_e32 v49, v48
	v_mov_b32_e32 v50, v48
	v_mov_b32_e32 v51, v48
	v_mov_b32_e32 v52, v48
	v_mov_b32_e32 v53, v48
	v_mov_b32_e32 v54, v48
	v_mov_b32_e32 v55, v48
	v_mov_b32_e32 v56, v48
	v_mov_b32_e32 v57, v48
	v_mov_b32_e32 v58, v48
	v_mov_b32_e32 v59, v48
	v_mov_b32_e32 v60, v48
	v_mov_b32_e32 v61, v48
	v_mov_b32_e32 v62, v48
	v_mov_b32_e32 v63, v48
	s_branch .LBB0_875
.LBB0_873:
	s_or_b64 exec, exec, s[8:9]
	global_load_dwordx4 v[160:163], v182, s[56:57] offset:256
	ds_read_b128 v[248:251], v203
	ds_read_b128 v[252:255], v203 offset:32
	v_add_f32_e32 v4, v82, v66
	v_add_u32_e32 v178, 0x6000, v178
	v_add_u32_e32 v180, 0x6000, v180
	v_add_u32_e32 v182, 0x100, v182
	v_add_f32_e32 v2, v80, v64
	v_add_f32_e32 v3, v81, v65
	v_add_f32_e32 v2, v3, v2
	v_add_f32_e32 v5, v83, v67
	v_add_f32_e32 v2, v4, v2
	v_add_f32_e32 v6, v84, v68
	v_add_f32_e32 v2, v5, v2
	v_add_f32_e32 v7, v85, v69
	v_add_f32_e32 v2, v6, v2
	v_max_f32_e32 v3, v96, v97
	v_add_f32_e32 v8, v86, v70
	v_add_f32_e32 v2, v7, v2
	v_max3_f32 v4, v98, v99, v113
	v_max3_f32 v3, v3, v112, v114
	v_add_f32_e32 v9, v87, v71
	v_add_f32_e32 v2, v8, v2
	v_max3_f32 v3, v3, v115, v100
	v_max3_f32 v4, v4, v102, v103
	v_add_f32_e32 v10, v88, v72
	v_add_f32_e32 v2, v9, v2
	v_max3_f32 v3, v3, v101, v116
	v_max3_f32 v4, v4, v118, v119
	v_add_f32_e32 v11, v89, v73
	v_add_f32_e32 v2, v10, v2
	v_max3_f32 v3, v3, v117, v104
	v_max3_f32 v4, v4, v106, v107
	v_add_f32_e32 v12, v90, v74
	v_add_f32_e32 v2, v11, v2
	v_max3_f32 v3, v3, v105, v120
	v_max3_f32 v4, v4, v122, v123
	v_add_f32_e32 v13, v91, v75
	v_add_f32_e32 v2, v12, v2
	v_max3_f32 v3, v3, v121, v108
	v_max3_f32 v4, v4, v110, v111
	v_add_f32_e32 v14, v92, v76
	v_add_f32_e32 v2, v13, v2
	v_max3_f32 v3, v3, v109, v124
	v_max3_f32 v4, v4, v126, v127
	v_add_f32_e32 v15, v93, v77
	v_add_f32_e32 v2, v14, v2
	v_max3_f32 v3, v3, v125, v4
	v_add_f32_e32 v64, v94, v78
	v_add_f32_e32 v2, v15, v2
	v_add_f32_e32 v65, v95, v79
	v_add_f32_e32 v2, v64, v2
	v_add_f32_e32 v2, v65, v2
	v_add_f32_e32 v188, v208, v2
	v_cmp_lt_f32_e32 vcc, s97, v3
	s_cbranch_vccnz .Lat2_resc_b
	v_mov_b32_e32 v210, v209

; DI float rowmax32(const f32x16& p0, const f32x16& p1) {
;     float a = fmaxf(fmaxf(p0[0], p0[1]), p1[0]), b = fmaxf(fmaxf(p0[2], p0[3]), p1[1]); a = fmaxf(fmaxf(a, p1[2]), p1[3]);
; #pragma unroll
;     for (int r = 4; r < 16; r += 4) { a = fmaxf(fmaxf(a, p0[r]), p0[r + 1]); b = fmaxf(fmaxf(b, p0[r + 2]), p0[r + 3]); a = fmaxf(fmaxf(a, p1[r]), p1[r + 1]); b = fmaxf(fmaxf(b, p1[r + 2]), p1[r + 3]); }
;     const float m = fmaxf(a, b);
;     const auto rr = __builtin_amdgcn_permlane32_swap(__float_as_uint(m), __float_as_uint(m), false, false);
;     return fmaxf(__uint_as_float(rr[0]), __uint_as_float(rr[1]));
.LBB0_880:
	s_or_b64 exec, exec, s[8:9]
	global_load_dwordx4 v[6:9], v182, s[56:57] offset:128
	ds_read_b128 v[112:115], v203 offset:13312
	ds_read_b128 v[116:119], v203 offset:13344
	v_max_f32_e32 v96, v64, v65
	v_max3_f32 v97, v66, v67, v81
	v_max3_f32 v96, v96, v80, v82
	v_max3_f32 v96, v96, v83, v68
	v_max3_f32 v97, v97, v70, v71
	v_max3_f32 v96, v96, v69, v84
	v_max3_f32 v97, v97, v86, v87
	v_max3_f32 v96, v96, v85, v72
	v_max3_f32 v97, v97, v74, v75
	v_max3_f32 v96, v96, v73, v88
	v_max3_f32 v97, v97, v90, v91
	v_max3_f32 v96, v96, v89, v76
	v_max3_f32 v97, v97, v78, v79
	v_max3_f32 v96, v96, v77, v92
	v_max3_f32 v97, v97, v94, v95
	v_max3_f32 v96, v96, v93, v97
	s_cmp_eq_u32 s76, 0
	s_cbranch_scc1 .Lat2_first
	v_cmp_lt_f32_e32 vcc, s97, v96
	s_cbranch_vccnz .Lat2_resc
	v_mov_b32_e32 v209, v210
